# gate GEMM epilogue first half: two late gate loads issued before the vmcnt wait (epilogue de-serialisation)
# baseline (speedup 1.0000x reference)
.LBB0_562:
	s_add_u32 s40, s6, s0
	ds_read_b128 v[112:115], v211
	ds_read_b128 v[116:119], v211 offset:1024
	ds_read_b128 v[128:131], v211 offset:2048
	ds_read_b128 v[132:135], v211 offset:3072
	s_addc_u32 s41, s7, s1
	s_add_u32 s40, s40, 0x10000100
	s_addc_u32 s41, s41, 0
	s_add_u32 s65, s62, s0
	s_addc_u32 s66, s63, s1
	s_cmpk_eq_i32 s0, 0x700
	s_cselect_b32 s43, s15, s41
	s_cselect_b32 s42, s14, s40
	s_cselect_b32 s41, s60, s66
	s_cselect_b32 s40, s61, s65
	v_lshl_add_u64 v[176:177], v[198:199], 0, s[0:1]
	s_add_i32 m0, s49, 0xc000
	ds_read_b128 v[144:147], v212
	ds_read_b128 v[148:151], v212 offset:1024
	ds_read_b128 v[152:155], v212 offset:2048
	ds_read_b128 v[156:159], v212 offset:3072
	ds_read_b128 v[160:163], v212 offset:4096
	ds_read_b128 v[164:167], v212 offset:5120
	ds_read_b128 v[168:171], v212 offset:6144
	ds_read_b128 v[172:175], v212 offset:7168
	global_load_lds_dwordx4 v[176:177], off
	v_lshl_add_u64 v[176:177], v[200:201], 0, s[0:1]
	s_add_i32 m0, s49, 0xe000
	s_nop 0
	global_load_lds_dwordx4 v[176:177], off
	s_waitcnt lgkmcnt(8)
	s_barrier
	s_waitcnt lgkmcnt(0)
	s_setprio 1
	s_waitcnt lgkmcnt(0)
	v_mfma_f32_16x16x32_bf16 v[140:143], v[112:115], v[144:147], v[140:143]
	v_mfma_f32_16x16x32_bf16 v[136:139], v[128:131], v[144:147], v[136:139]
	v_mfma_f32_16x16x32_bf16 v[108:111], v[112:115], v[152:155], v[108:111]
	v_mfma_f32_16x16x32_bf16 v[104:107], v[128:131], v[152:155], v[104:107]
	v_mfma_f32_16x16x32_bf16 v[92:95], v[112:115], v[160:163], v[92:95]
	v_mfma_f32_16x16x32_bf16 v[88:91], v[128:131], v[160:163], v[88:91]
	v_mfma_f32_16x16x32_bf16 v[76:79], v[112:115], v[168:171], v[76:79]
	v_mfma_f32_16x16x32_bf16 v[72:75], v[128:131], v[168:171], v[72:75]
	v_mfma_f32_16x16x32_bf16 v[140:143], v[116:119], v[148:151], v[140:143]
	v_mfma_f32_16x16x32_bf16 v[136:139], v[132:135], v[148:151], v[136:139]
	v_mfma_f32_16x16x32_bf16 v[108:111], v[116:119], v[156:159], v[108:111]
	v_mfma_f32_16x16x32_bf16 v[104:107], v[132:135], v[156:159], v[104:107]
	v_mfma_f32_16x16x32_bf16 v[92:95], v[116:119], v[164:167], v[92:95]
	v_mfma_f32_16x16x32_bf16 v[88:91], v[132:135], v[164:167], v[88:91]
	v_mfma_f32_16x16x32_bf16 v[76:79], v[116:119], v[172:175], v[76:79]
	v_mfma_f32_16x16x32_bf16 v[72:75], v[132:135], v[172:175], v[72:75]
	s_setprio 0
	s_barrier
	s_add_i32 s65, s45, s3
	v_lshl_add_u64 v[206:207], s[40:41], 0, v[194:195]
	s_mov_b32 m0, s65
	ds_read_b128 v[176:179], v213
	ds_read_b128 v[180:183], v213 offset:1024
	ds_read_b128 v[202:205], v213 offset:2048
	ds_read_b128 v[216:219], v213 offset:3072
	global_load_lds_dwordx4 v[206:207], off
	v_lshl_add_u64 v[220:221], s[40:41], 0, v[190:191]
	s_add_i32 m0, s65, 0x2000
	s_nop 0
	global_load_lds_dwordx4 v[220:221], off
	s_barrier
	s_waitcnt lgkmcnt(0)
	s_setprio 1
	s_waitcnt lgkmcnt(0)
	v_mfma_f32_16x16x32_bf16 v[124:127], v[176:179], v[144:147], v[124:127]
	v_mfma_f32_16x16x32_bf16 v[120:123], v[202:205], v[144:147], v[120:123]
	v_mfma_f32_16x16x32_bf16 v[100:103], v[176:179], v[152:155], v[100:103]
	v_mfma_f32_16x16x32_bf16 v[96:99], v[202:205], v[152:155], v[96:99]
	v_mfma_f32_16x16x32_bf16 v[84:87], v[176:179], v[160:163], v[84:87]
	v_mfma_f32_16x16x32_bf16 v[80:83], v[202:205], v[160:163], v[80:83]
	v_mfma_f32_16x16x32_bf16 v[68:71], v[176:179], v[168:171], v[68:71]
	v_mfma_f32_16x16x32_bf16 v[64:67], v[202:205], v[168:171], v[64:67]
	v_mfma_f32_16x16x32_bf16 v[124:127], v[180:183], v[148:151], v[124:127]
	v_mfma_f32_16x16x32_bf16 v[120:123], v[216:219], v[148:151], v[120:123]
	v_mfma_f32_16x16x32_bf16 v[100:103], v[180:183], v[156:159], v[100:103]
	v_mfma_f32_16x16x32_bf16 v[96:99], v[216:219], v[156:159], v[96:99]
	v_mfma_f32_16x16x32_bf16 v[84:87], v[180:183], v[164:167], v[84:87]
	v_mfma_f32_16x16x32_bf16 v[80:83], v[216:219], v[164:167], v[80:83]
	v_mfma_f32_16x16x32_bf16 v[68:71], v[180:183], v[172:175], v[68:71]
	v_mfma_f32_16x16x32_bf16 v[64:67], v[216:219], v[172:175], v[64:67]
	s_setprio 0
	s_mov_b32 m0, s49
	v_lshl_add_u64 v[222:223], s[42:43], 0, v[196:197]
	s_barrier
	ds_read_b128 v[144:147], v212 offset:16384
	ds_read_b128 v[148:151], v212 offset:17408
	ds_read_b128 v[152:155], v212 offset:18432
	ds_read_b128 v[156:159], v212 offset:19456
	ds_read_b128 v[160:163], v212 offset:20480
	ds_read_b128 v[164:167], v212 offset:21504
	ds_read_b128 v[168:171], v212 offset:22528
	ds_read_b128 v[172:175], v212 offset:23552
	global_load_lds_dwordx4 v[222:223], off
	v_lshl_add_u64 v[224:225], s[42:43], 0, v[192:193]
	s_mov_b32 m0, s50
	s_nop 0
	global_load_lds_dwordx4 v[224:225], off
	s_barrier
	s_waitcnt lgkmcnt(0)
	s_setprio 1
	s_waitcnt lgkmcnt(0)
	v_mfma_f32_16x16x32_bf16 v[60:63], v[112:115], v[144:147], v[60:63]
	v_mfma_f32_16x16x32_bf16 v[56:59], v[128:131], v[144:147], v[56:59]
	v_mfma_f32_16x16x32_bf16 v[44:47], v[112:115], v[152:155], v[44:47]
	v_mfma_f32_16x16x32_bf16 v[40:43], v[128:131], v[152:155], v[40:43]
	v_mfma_f32_16x16x32_bf16 v[28:31], v[112:115], v[160:163], v[28:31]
	v_mfma_f32_16x16x32_bf16 v[24:27], v[128:131], v[160:163], v[24:27]
	v_mfma_f32_16x16x32_bf16 v[12:15], v[112:115], v[168:171], v[12:15]
	v_mfma_f32_16x16x32_bf16 v[8:11], v[128:131], v[168:171], v[8:11]
	v_mfma_f32_16x16x32_bf16 v[60:63], v[116:119], v[148:151], v[60:63]
	v_mfma_f32_16x16x32_bf16 v[56:59], v[132:135], v[148:151], v[56:59]
	v_mfma_f32_16x16x32_bf16 v[44:47], v[116:119], v[156:159], v[44:47]
	v_mfma_f32_16x16x32_bf16 v[40:43], v[132:135], v[156:159], v[40:43]
	v_mfma_f32_16x16x32_bf16 v[28:31], v[116:119], v[164:167], v[28:31]
	v_mfma_f32_16x16x32_bf16 v[24:27], v[132:135], v[164:167], v[24:27]
	v_mfma_f32_16x16x32_bf16 v[12:15], v[116:119], v[172:175], v[12:15]
	v_mfma_f32_16x16x32_bf16 v[8:11], v[132:135], v[172:175], v[8:11]
	s_setprio 0
	s_barrier
	s_add_u32 s66, s40, 0x40000
	s_addc_u32 s67, s41, 0
	s_add_i32 s65, s46, s3
	v_lshl_add_u64 v[112:113], s[66:67], 0, v[194:195]
	s_mov_b32 m0, s65
	s_nop 0
	global_load_lds_dwordx4 v[112:113], off
	v_lshl_add_u64 v[112:113], s[66:67], 0, v[190:191]
	s_add_i32 m0, s65, 0x2000
	s_nop 0
	global_load_lds_dwordx4 v[112:113], off
	s_waitcnt vmcnt(6)
	s_barrier
	s_setprio 1
	v_mfma_f32_16x16x32_bf16 v[52:55], v[176:179], v[144:147], v[52:55]
	v_mfma_f32_16x16x32_bf16 v[48:51], v[202:205], v[144:147], v[48:51]
	v_mfma_f32_16x16x32_bf16 v[36:39], v[176:179], v[152:155], v[36:39]
	v_mfma_f32_16x16x32_bf16 v[32:35], v[202:205], v[152:155], v[32:35]
	v_mfma_f32_16x16x32_bf16 v[20:23], v[176:179], v[160:163], v[20:23]
	v_mfma_f32_16x16x32_bf16 v[16:19], v[202:205], v[160:163], v[16:19]
	v_mfma_f32_16x16x32_bf16 v[4:7], v[176:179], v[168:171], v[4:7]
	v_mfma_f32_16x16x32_bf16 v[0:3], v[202:205], v[168:171], v[0:3]
	v_mfma_f32_16x16x32_bf16 v[52:55], v[180:183], v[148:151], v[52:55]
	v_mfma_f32_16x16x32_bf16 v[48:51], v[216:219], v[148:151], v[48:51]
	v_mfma_f32_16x16x32_bf16 v[36:39], v[180:183], v[156:159], v[36:39]
	v_mfma_f32_16x16x32_bf16 v[32:35], v[216:219], v[156:159], v[32:35]
	v_mfma_f32_16x16x32_bf16 v[20:23], v[180:183], v[164:167], v[20:23]
	v_mfma_f32_16x16x32_bf16 v[16:19], v[216:219], v[164:167], v[16:19]
	v_mfma_f32_16x16x32_bf16 v[4:7], v[180:183], v[172:175], v[4:7]
	v_mfma_f32_16x16x32_bf16 v[0:3], v[216:219], v[172:175], v[0:3]
	s_setprio 0
	v_add_u32_e32 v132, s47, v210
	s_barrier
	ds_read_b128 v[112:115], v132
	ds_read_b128 v[116:119], v132 offset:1024
	ds_read_b128 v[128:131], v132 offset:2048
	ds_read_b128 v[132:135], v132 offset:3072
	s_add_u32 s42, s42, 0x40000
	s_addc_u32 s43, s43, 0
	s_mov_b32 m0, s51
	v_lshl_add_u64 v[176:177], s[42:43], 0, v[196:197]
	ds_read_b128 v[144:147], v212 offset:32768
	ds_read_b128 v[148:151], v212 offset:33792
	ds_read_b128 v[152:155], v212 offset:34816
	ds_read_b128 v[156:159], v212 offset:35840
	ds_read_b128 v[160:163], v212 offset:36864
	ds_read_b128 v[164:167], v212 offset:37888
	ds_read_b128 v[168:171], v212 offset:38912
	ds_read_b128 v[172:175], v212 offset:39936
	global_load_lds_dwordx4 v[176:177], off
	v_lshl_add_u64 v[176:177], s[42:43], 0, v[192:193]
	s_mov_b32 m0, s52
	s_nop 0
	global_load_lds_dwordx4 v[176:177], off
	s_waitcnt lgkmcnt(8)
	s_barrier
	s_waitcnt lgkmcnt(0)
	s_setprio 1
	s_waitcnt lgkmcnt(0)
	v_mfma_f32_16x16x32_bf16 v[140:143], v[112:115], v[144:147], v[140:143]
	v_mfma_f32_16x16x32_bf16 v[136:139], v[128:131], v[144:147], v[136:139]
	v_mfma_f32_16x16x32_bf16 v[108:111], v[112:115], v[152:155], v[108:111]
	v_mfma_f32_16x16x32_bf16 v[104:107], v[128:131], v[152:155], v[104:107]
	v_mfma_f32_16x16x32_bf16 v[92:95], v[112:115], v[160:163], v[92:95]
	v_mfma_f32_16x16x32_bf16 v[88:91], v[128:131], v[160:163], v[88:91]
	v_mfma_f32_16x16x32_bf16 v[76:79], v[112:115], v[168:171], v[76:79]
	v_mfma_f32_16x16x32_bf16 v[72:75], v[128:131], v[168:171], v[72:75]
	v_mfma_f32_16x16x32_bf16 v[140:143], v[116:119], v[148:151], v[140:143]
	v_mfma_f32_16x16x32_bf16 v[136:139], v[132:135], v[148:151], v[136:139]
	v_mfma_f32_16x16x32_bf16 v[108:111], v[116:119], v[156:159], v[108:111]
	v_mfma_f32_16x16x32_bf16 v[104:107], v[132:135], v[156:159], v[104:107]
	v_mfma_f32_16x16x32_bf16 v[92:95], v[116:119], v[164:167], v[92:95]
	v_mfma_f32_16x16x32_bf16 v[88:91], v[132:135], v[164:167], v[88:91]
	v_mfma_f32_16x16x32_bf16 v[76:79], v[116:119], v[172:175], v[76:79]
	v_mfma_f32_16x16x32_bf16 v[72:75], v[132:135], v[172:175], v[72:75]
	s_setprio 0
	s_barrier
	s_add_i32 s42, s47, s3
	v_add_u32_e32 v215, s48, v210
	v_lshl_add_u64 v[206:207], v[206:207], 0, s[20:21]
	s_mov_b32 m0, s42
	ds_read_b128 v[176:179], v215
	ds_read_b128 v[180:183], v215 offset:1024
	ds_read_b128 v[202:205], v215 offset:2048
	ds_read_b128 v[216:219], v215 offset:3072
	global_load_lds_dwordx4 v[206:207], off
	v_lshl_add_u64 v[206:207], v[220:221], 0, s[20:21]
	s_add_i32 m0, s42, 0x2000
	s_nop 0
	global_load_lds_dwordx4 v[206:207], off
	s_barrier
	s_waitcnt lgkmcnt(0)
	s_setprio 1
	s_waitcnt lgkmcnt(0)
	v_mfma_f32_16x16x32_bf16 v[124:127], v[176:179], v[144:147], v[124:127]
	v_mfma_f32_16x16x32_bf16 v[120:123], v[202:205], v[144:147], v[120:123]
	v_mfma_f32_16x16x32_bf16 v[100:103], v[176:179], v[152:155], v[100:103]
	v_mfma_f32_16x16x32_bf16 v[96:99], v[202:205], v[152:155], v[96:99]
	v_mfma_f32_16x16x32_bf16 v[84:87], v[176:179], v[160:163], v[84:87]
	v_mfma_f32_16x16x32_bf16 v[80:83], v[202:205], v[160:163], v[80:83]
	v_mfma_f32_16x16x32_bf16 v[68:71], v[176:179], v[168:171], v[68:71]
	v_mfma_f32_16x16x32_bf16 v[64:67], v[202:205], v[168:171], v[64:67]
	v_mfma_f32_16x16x32_bf16 v[124:127], v[180:183], v[148:151], v[124:127]
	v_mfma_f32_16x16x32_bf16 v[120:123], v[216:219], v[148:151], v[120:123]
	v_mfma_f32_16x16x32_bf16 v[100:103], v[180:183], v[156:159], v[100:103]
	v_mfma_f32_16x16x32_bf16 v[96:99], v[216:219], v[156:159], v[96:99]
	v_mfma_f32_16x16x32_bf16 v[84:87], v[180:183], v[164:167], v[84:87]
	v_mfma_f32_16x16x32_bf16 v[80:83], v[216:219], v[164:167], v[80:83]
	v_mfma_f32_16x16x32_bf16 v[68:71], v[180:183], v[172:175], v[68:71]
	v_mfma_f32_16x16x32_bf16 v[64:67], v[216:219], v[172:175], v[64:67]
	s_setprio 0
	s_mov_b32 m0, s56
	v_lshl_add_u64 v[206:207], v[222:223], 0, s[20:21]
	s_barrier
	ds_read_b128 v[144:147], v212 offset:49152
	ds_read_b128 v[148:151], v212 offset:50176
	ds_read_b128 v[152:155], v212 offset:51200
	ds_read_b128 v[156:159], v212 offset:52224
	ds_read_b128 v[160:163], v212 offset:53248
	ds_read_b128 v[164:167], v212 offset:54272
	ds_read_b128 v[168:171], v212 offset:55296
	ds_read_b128 v[172:175], v212 offset:56320
	global_load_lds_dwordx4 v[206:207], off
	v_lshl_add_u64 v[206:207], v[224:225], 0, s[20:21]
	s_mov_b32 m0, s57
	s_nop 0
	global_load_lds_dwordx4 v[206:207], off
	s_barrier
	s_waitcnt lgkmcnt(0)
	s_setprio 1
	s_waitcnt lgkmcnt(0)
	v_mfma_f32_16x16x32_bf16 v[60:63], v[112:115], v[144:147], v[60:63]
	v_mfma_f32_16x16x32_bf16 v[56:59], v[128:131], v[144:147], v[56:59]
	v_mfma_f32_16x16x32_bf16 v[44:47], v[112:115], v[152:155], v[44:47]
	v_mfma_f32_16x16x32_bf16 v[40:43], v[128:131], v[152:155], v[40:43]
	v_mfma_f32_16x16x32_bf16 v[28:31], v[112:115], v[160:163], v[28:31]
	v_mfma_f32_16x16x32_bf16 v[24:27], v[128:131], v[160:163], v[24:27]
	v_mfma_f32_16x16x32_bf16 v[12:15], v[112:115], v[168:171], v[12:15]
	v_mfma_f32_16x16x32_bf16 v[8:11], v[128:131], v[168:171], v[8:11]
	v_mfma_f32_16x16x32_bf16 v[60:63], v[116:119], v[148:151], v[60:63]
	v_mfma_f32_16x16x32_bf16 v[56:59], v[132:135], v[148:151], v[56:59]
	v_mfma_f32_16x16x32_bf16 v[44:47], v[116:119], v[156:159], v[44:47]
	v_mfma_f32_16x16x32_bf16 v[40:43], v[132:135], v[156:159], v[40:43]
	v_mfma_f32_16x16x32_bf16 v[28:31], v[116:119], v[164:167], v[28:31]
	v_mfma_f32_16x16x32_bf16 v[24:27], v[132:135], v[164:167], v[24:27]
	v_mfma_f32_16x16x32_bf16 v[12:15], v[116:119], v[172:175], v[12:15]
	v_mfma_f32_16x16x32_bf16 v[8:11], v[132:135], v[172:175], v[8:11]
	s_setprio 0
	s_barrier
	s_add_u32 s40, s40, 0x40080
	s_addc_u32 s41, s41, 0
	s_add_i32 s42, s48, s3
	v_lshl_add_u64 v[112:113], s[40:41], 0, v[194:195]
	s_mov_b32 m0, s42
	s_nop 0
	global_load_lds_dwordx4 v[112:113], off
	v_lshl_add_u64 v[112:113], s[40:41], 0, v[190:191]
	s_add_i32 m0, s42, 0x2000
	s_nop 0
	global_load_lds_dwordx4 v[112:113], off
	s_waitcnt vmcnt(6)
	s_barrier
	s_setprio 1
	v_mfma_f32_16x16x32_bf16 v[52:55], v[176:179], v[144:147], v[52:55]
	v_mfma_f32_16x16x32_bf16 v[48:51], v[202:205], v[144:147], v[48:51]
	v_mfma_f32_16x16x32_bf16 v[36:39], v[176:179], v[152:155], v[36:39]
	v_mfma_f32_16x16x32_bf16 v[32:35], v[202:205], v[152:155], v[32:35]
	v_mfma_f32_16x16x32_bf16 v[20:23], v[176:179], v[160:163], v[20:23]
	v_mfma_f32_16x16x32_bf16 v[16:19], v[202:205], v[160:163], v[16:19]
	v_mfma_f32_16x16x32_bf16 v[4:7], v[176:179], v[168:171], v[4:7]
	v_mfma_f32_16x16x32_bf16 v[0:3], v[202:205], v[168:171], v[0:3]
	v_mfma_f32_16x16x32_bf16 v[52:55], v[180:183], v[148:151], v[52:55]
	v_mfma_f32_16x16x32_bf16 v[48:51], v[216:219], v[148:151], v[48:51]
	v_mfma_f32_16x16x32_bf16 v[36:39], v[180:183], v[156:159], v[36:39]
	v_mfma_f32_16x16x32_bf16 v[32:35], v[216:219], v[156:159], v[32:35]
	v_mfma_f32_16x16x32_bf16 v[20:23], v[180:183], v[164:167], v[20:23]
	v_mfma_f32_16x16x32_bf16 v[16:19], v[216:219], v[164:167], v[16:19]
	v_mfma_f32_16x16x32_bf16 v[4:7], v[180:183], v[172:175], v[4:7]
	v_mfma_f32_16x16x32_bf16 v[0:3], v[216:219], v[172:175], v[0:3]
	s_setprio 0
	s_add_i32 s64, s64, 2
	s_add_u32 s0, s0, 0x100
	s_addc_u32 s1, s1, 0
	s_cmp_gt_u32 s64, 13
	s_barrier
	s_cbranch_scc0 .LBB0_562
	v_mov_b32_e32 v112, v208
	v_mov_b32_e32 v118, v209
	s_lshl_b32 s0, s59, 8
	v_add_u32_e32 v215, s54, v112
	v_add_u32_e32 v204, s44, v215
	s_or_b32 s0, s0, s55
	v_lshl_add_u32 v202, v118, 3, s0
	v_ashrrev_i32_e32 v205, 31, v204
	v_ashrrev_i32_e32 v203, 31, v202
	v_lshlrev_b64 v[112:113], 10, v[204:205]
	v_lshl_add_u64 v[112:113], v[112:113], 0, v[202:203]
	v_lshlrev_b64 v[112:113], 1, v[112:113]
	v_lshl_add_u64 v[114:115], s[24:25], 0, v[112:113]
	global_load_dwordx4 v[218:221], v[114:115], off
	v_lshl_add_u64 v[116:117], s[26:27], 0, v[112:113]
	global_load_dwordx4 v[222:225], v[116:117], off
	v_lshl_add_u32 v217, v215, 2, 0
	v_add_u32_e32 v216, 0x20000, v217
	ds_read_b32 v130, v216
	global_load_dwordx4 v[176:179], v[116:117], off offset:256
	global_load_dwordx4 v[180:183], v[114:115], off offset:256
	v_cmp_eq_u32_e32 vcc, 0, v118
	v_lshl_add_u64 v[118:119], v[112:113], 0, s[8:9]
	v_lshl_add_u64 v[128:129], v[112:113], 0, s[22:23]
	v_lshl_add_u64 v[114:115], s[26:27], 0, v[118:119]
	v_lshl_add_u64 v[112:113], v[112:113], 0, s[28:29]
	v_lshl_add_u64 v[116:117], s[24:25], 0, v[118:119]
	v_lshl_add_u64 v[118:119], s[26:27], 0, v[128:129]
	v_lshl_add_u64 v[128:129], s[24:25], 0, v[128:129]
	global_load_dwordx4 v[168:171], v[114:115], off
	global_load_dwordx4 v[160:163], v[114:115], off offset:256
	global_load_dwordx4 v[172:175], v[116:117], off
	global_load_dwordx4 v[164:167], v[116:117], off offset:256
	global_load_dwordx4 v[152:155], v[118:119], off
	global_load_dwordx4 v[144:147], v[118:119], off offset:256
	global_load_dwordx4 v[156:159], v[128:129], off
	global_load_dwordx4 v[148:151], v[128:129], off offset:256
	v_lshl_add_u64 v[132:133], s[26:27], 0, v[112:113]
	v_lshl_add_u64 v[226:227], s[24:25], 0, v[112:113]
	s_waitcnt lgkmcnt(0)
	v_fmamk_f32 v112, v130, 0x3a800000, v214
	global_load_dwordx4 v[128:131], v[132:133], off
	global_load_dwordx4 v[116:119], v[226:227], off offset:256
	v_mul_f32_e32 v113, 0x4b800000, v112
	v_cmp_gt_f32_e64 s[0:1], s58, v112
	v_lshlrev_b64 v[206:207], 11, v[204:205]
	s_waitcnt vmcnt(2)
	v_and_b32_e32 v229, 0xffff0000, v220
	v_cndmask_b32_e64 v112, v112, v113, s[0:1]
	v_rsq_f32_e32 v228, v112
	global_load_dwordx4 v[112:115], v[132:133], off offset:256
	s_nop 0
	global_load_dwordx4 v[132:135], v[226:227], off
	v_and_b32_e32 v227, 0xffff0000, v222
	v_lshlrev_b32_e32 v230, 16, v224
	v_mul_f32_e32 v226, 0x45800000, v228
	v_cndmask_b32_e64 v232, v228, v226, s[0:1]
	v_mul_f32_e32 v140, v140, v232
	v_mul_f32_e32 v136, v136, v232
	v_mul_f32_e32 v141, v141, v232
	v_mul_f32_e32 v142, v142, v232
	v_mul_f32_e32 v140, 0xbfb8aa3b, v140
	v_mul_f32_e32 v136, 0xbfb8aa3b, v136
	v_mul_f32_e32 v137, v137, v232
	v_mul_f32_e32 v141, 0xbfb8aa3b, v141
	v_mul_f32_e32 v142, 0xbfb8aa3b, v142
	v_exp_f32_e32 v140, v140
	v_exp_f32_e32 v136, v136
	v_mul_f32_e32 v137, 0xbfb8aa3b, v137
	v_exp_f32_e32 v141, v141
	v_exp_f32_e32 v142, v142
	v_exp_f32_e32 v137, v137
	v_mul_f32_e32 v143, v143, v232
	v_mul_f32_e32 v138, v138, v232
	v_mul_f32_e32 v233, 0xbfb8aa3b, v143
	v_add_f32_e32 v140, 1.0, v140
	v_add_f32_e32 v143, 1.0, v136
	v_mul_f32_e32 v139, v139, v232
	v_mul_f32_e32 v138, 0xbfb8aa3b, v138
	v_add_f32_e32 v141, 1.0, v141
	v_add_f32_e32 v234, 1.0, v142
	v_rcp_f32_e32 v136, v140
	v_rcp_f32_e32 v140, v143
	v_lshlrev_b32_e32 v142, 16, v218
	v_and_b32_e32 v143, 0xffff0000, v218
	v_exp_f32_e32 v218, v233
	v_mul_f32_e32 v139, 0xbfb8aa3b, v139
	v_exp_f32_e32 v138, v138
	v_add_f32_e32 v226, 1.0, v137
	v_rcp_f32_e32 v137, v141
	v_exp_f32_e32 v139, v139
	v_mul_f32_e32 v124, v124, v232
	v_mul_f32_e32 v125, v125, v232
	v_mul_f32_e32 v124, 0xbfb8aa3b, v124
	v_mul_f32_e32 v120, v120, v232
	v_mul_f32_e32 v125, 0xbfb8aa3b, v125
	v_mul_f32_e32 v121, v121, v232
	v_rcp_f32_e32 v141, v226
	v_lshlrev_b32_e32 v226, 16, v222
	v_add_f32_e32 v218, 1.0, v218
	v_exp_f32_e32 v124, v124
	v_mul_f32_e32 v120, 0xbfb8aa3b, v120
	v_exp_f32_e32 v125, v125
	v_mul_f32_e32 v121, 0xbfb8aa3b, v121
	v_mul_f32_e32 v126, v126, v232
	v_mul_f32_e32 v127, v127, v232
	v_pk_fma_f32 v[136:137], v[136:137], v[142:143], v[226:227]
	v_rcp_f32_e32 v226, v234
	v_add_f32_e32 v138, 1.0, v138
	v_rcp_f32_e32 v227, v218
	v_add_f32_e32 v139, 1.0, v139
	v_exp_f32_e32 v120, v120
	v_exp_f32_e32 v121, v121
	v_mul_f32_e32 v126, 0xbfb8aa3b, v126
	v_mul_f32_e32 v122, v122, v232
	v_mul_f32_e32 v127, 0xbfb8aa3b, v127
	v_mul_f32_e32 v123, v123, v232
	v_rcp_f32_e32 v138, v138
	v_rcp_f32_e32 v139, v139
	v_exp_f32_e32 v126, v126
	v_mul_f32_e32 v122, 0xbfb8aa3b, v122
	v_exp_f32_e32 v127, v127
	v_mul_f32_e32 v123, 0xbfb8aa3b, v123
	v_exp_f32_e32 v122, v122
	v_exp_f32_e32 v123, v123
	v_lshlrev_b32_e32 v218, 16, v219
	v_and_b32_e32 v219, 0xffff0000, v219
	v_lshlrev_b32_e32 v222, 16, v223
	v_and_b32_e32 v223, 0xffff0000, v223
	v_add_f32_e32 v124, 1.0, v124
	v_add_f32_e32 v125, 1.0, v125
	v_lshlrev_b32_e32 v228, 16, v220
	v_and_b32_e32 v231, 0xffff0000, v224
	v_pk_fma_f32 v[218:219], v[226:227], v[218:219], v[222:223]
	v_lshlrev_b32_e32 v220, 16, v221
	v_and_b32_e32 v221, 0xffff0000, v221
	v_lshlrev_b32_e32 v222, 16, v225
	v_and_b32_e32 v223, 0xffff0000, v225
	v_rcp_f32_e32 v124, v124
	v_add_f32_e32 v120, 1.0, v120
	v_rcp_f32_e32 v125, v125
	v_add_f32_e32 v121, 1.0, v121
	v_pk_fma_f32 v[140:141], v[140:141], v[228:229], v[230:231]
	v_pk_fma_f32 v[220:221], v[138:139], v[220:221], v[222:223]
	v_rcp_f32_e32 v120, v120
	v_rcp_f32_e32 v121, v121
	v_add_f32_e32 v126, 1.0, v126
	v_add_f32_e32 v127, 1.0, v127
	v_pk_mul_f32 v[142:143], v[140:141], v[140:141]
	v_pk_mul_f32 v[138:139], v[220:221], v[220:221]
	v_rcp_f32_e32 v126, v126
	v_add_f32_e32 v122, 1.0, v122
	v_rcp_f32_e32 v127, v127
	v_add_f32_e32 v123, 1.0, v123
	v_pk_fma_f32 v[142:143], v[136:137], v[136:137], v[142:143]
	v_pk_fma_f32 v[222:223], v[218:219], v[218:219], v[138:139]
	v_cvt_pk_bf16_f32 v136, v136, v137
	v_cvt_pk_bf16_f32 v137, v218, v219
	v_cvt_pk_bf16_f32 v138, v140, v141
	v_lshlrev_b32_e32 v140, 16, v180
	v_and_b32_e32 v141, 0xffff0000, v180
	v_lshlrev_b32_e32 v218, 16, v176
	v_and_b32_e32 v219, 0xffff0000, v176
	v_rcp_f32_e32 v122, v122
	v_rcp_f32_e32 v123, v123
	v_pk_fma_f32 v[124:125], v[124:125], v[140:141], v[218:219]
	v_lshlrev_b32_e32 v140, 16, v182
	v_and_b32_e32 v141, 0xffff0000, v182
	v_lshlrev_b32_e32 v218, 16, v178
	v_and_b32_e32 v219, 0xffff0000, v178
	v_pk_fma_f32 v[140:141], v[120:121], v[140:141], v[218:219]
	v_lshlrev_b32_e32 v180, 16, v181
	v_and_b32_e32 v181, 0xffff0000, v181
	v_lshlrev_b32_e32 v176, 16, v177
	v_and_b32_e32 v177, 0xffff0000, v177
	v_add_f32_e32 v142, v142, v143
	v_pk_mul_f32 v[120:121], v[140:141], v[140:141]
	v_pk_fma_f32 v[126:127], v[126:127], v[180:181], v[176:177]
	v_lshlrev_b32_e32 v176, 16, v183
	v_and_b32_e32 v177, 0xffff0000, v183
	v_lshlrev_b32_e32 v178, 16, v179
	v_and_b32_e32 v179, 0xffff0000, v179
	v_add_f32_e32 v142, v222, v142
	v_pk_fma_f32 v[120:121], v[124:125], v[124:125], v[120:121]
	v_pk_fma_f32 v[176:177], v[122:123], v[176:177], v[178:179]
	v_add_f32_e32 v142, v223, v142
	v_pk_mul_f32 v[122:123], v[176:177], v[176:177]
	v_add_f32_e32 v120, v120, v142
	v_pk_fma_f32 v[122:123], v[126:127], v[126:127], v[122:123]
	v_add_f32_e32 v120, v121, v120
	v_add_f32_e32 v120, v122, v120
	v_add_f32_e32 v123, v123, v120
	ds_bpermute_b32 v178, v187, v123
	v_lshl_add_u64 v[120:121], s[18:19], 0, v[206:207]
	v_lshl_add_u64 v[142:143], v[202:203], 1, v[120:121]
	v_cvt_pk_bf16_f32 v139, v220, v221
	v_cvt_pk_bf16_f32 v122, v124, v125
	s_waitcnt lgkmcnt(0)
	v_add_f32_e32 v120, v123, v178
	ds_bpermute_b32 v121, v189, v120
	v_cvt_pk_bf16_f32 v123, v126, v127
	v_cvt_pk_bf16_f32 v124, v140, v141
	v_cvt_pk_bf16_f32 v125, v176, v177
	global_store_dwordx4 v[142:143], v[136:139], off
	global_store_dwordx4 v[142:143], v[122:125], off offset:256
	s_and_saveexec_b64 s[0:1], vcc
	s_cbranch_execz .LBB0_565
	s_waitcnt lgkmcnt(0)
	v_add_f32_e32 v120, v120, v121
	v_add_u32_e32 v121, 0x20400, v217
	ds_add_f32 v121, v120

.LBB0_569:
	s_or_b64 exec, exec, s[0:1]
	s_waitcnt lgkmcnt(0)
	ds_read_b32 v81, v216 offset:192
	s_waitcnt vmcnt(6)
	v_and_b32_e32 v85, 0xffff0000, v132
	v_lshlrev_b32_e32 v86, 16, v128
	v_and_b32_e32 v87, 0xffff0000, v128
	v_lshlrev_b32_e32 v88, 16, v129
	s_waitcnt lgkmcnt(0)
	v_fmamk_f32 v81, v81, 0x3a800000, v214
	v_mul_f32_e32 v82, 0x4b800000, v81
	v_cmp_gt_f32_e64 s[0:1], s58, v81
	v_and_b32_e32 v89, 0xffff0000, v129
	v_add_u32_e32 v80, 48, v215
	v_cndmask_b32_e64 v81, v81, v82, s[0:1]
	v_rsq_f32_e32 v81, v81
	v_add_u32_e32 v82, s44, v80
	v_ashrrev_i32_e32 v83, 31, v82
	v_lshlrev_b64 v[82:83], 11, v[82:83]
	v_mul_f32_e32 v84, 0x45800000, v81
	v_cndmask_b32_e64 v81, v81, v84, s[0:1]
	v_mul_f32_e32 v76, v76, v81
	v_mul_f32_e32 v77, v77, v81
	v_mul_f32_e32 v72, v72, v81
	v_mul_f32_e32 v76, 0xbfb8aa3b, v76
	v_mul_f32_e32 v77, 0xbfb8aa3b, v77
	v_mul_f32_e32 v73, v73, v81
	v_exp_f32_e32 v76, v76
	v_mul_f32_e32 v72, 0xbfb8aa3b, v72
	v_exp_f32_e32 v77, v77
	v_mul_f32_e32 v73, 0xbfb8aa3b, v73
	v_exp_f32_e32 v72, v72
	v_exp_f32_e32 v73, v73
	v_add_f32_e32 v76, 1.0, v76
	v_add_f32_e32 v77, 1.0, v77
	v_rcp_f32_e32 v76, v76
	v_add_f32_e32 v72, 1.0, v72
	v_rcp_f32_e32 v77, v77
	v_add_f32_e32 v73, 1.0, v73
	v_rcp_f32_e32 v72, v72
	v_rcp_f32_e32 v73, v73
	v_lshlrev_b32_e32 v84, 16, v132
	v_pk_fma_f32 v[76:77], v[76:77], v[84:85], v[86:87]
	v_lshlrev_b32_e32 v84, 16, v134
	v_and_b32_e32 v85, 0xffff0000, v134
	v_lshlrev_b32_e32 v86, 16, v130
	v_and_b32_e32 v87, 0xffff0000, v130
	v_mul_f32_e32 v78, v78, v81
	v_mul_f32_e32 v78, 0xbfb8aa3b, v78
	v_pk_fma_f32 v[84:85], v[72:73], v[84:85], v[86:87]
	v_exp_f32_e32 v78, v78
	v_pk_mul_f32 v[72:73], v[84:85], v[84:85]
	v_mul_f32_e32 v75, v75, v81
	v_pk_fma_f32 v[86:87], v[76:77], v[76:77], v[72:73]
	v_mul_f32_e32 v73, v74, v81
	v_mul_f32_e32 v73, 0xbfb8aa3b, v73
	v_mul_f32_e32 v74, v79, v81
	v_exp_f32_e32 v73, v73
	v_mul_f32_e32 v74, 0xbfb8aa3b, v74
	v_add_f32_e32 v72, 1.0, v78
	v_exp_f32_e32 v78, v74
	v_add_f32_e32 v73, 1.0, v73
	v_rcp_f32_e32 v74, v73
	v_mul_f32_e32 v75, 0xbfb8aa3b, v75
	v_add_f32_e32 v73, 1.0, v78
	v_rcp_f32_e32 v72, v72
	v_rcp_f32_e32 v73, v73
	v_exp_f32_e32 v75, v75
	v_mul_f32_e32 v68, v68, v81
	v_mul_f32_e32 v69, v69, v81
	v_mul_f32_e32 v68, 0xbfb8aa3b, v68
	v_mul_f32_e32 v64, v64, v81
	v_mul_f32_e32 v69, 0xbfb8aa3b, v69
	v_mul_f32_e32 v65, v65, v81
	v_lshlrev_b32_e32 v78, 16, v133
	v_and_b32_e32 v79, 0xffff0000, v133
	v_exp_f32_e32 v68, v68
	v_mul_f32_e32 v64, 0xbfb8aa3b, v64
	v_exp_f32_e32 v69, v69
	v_mul_f32_e32 v65, 0xbfb8aa3b, v65
	v_mul_f32_e32 v70, v70, v81
	v_mul_f32_e32 v71, v71, v81
	v_pk_fma_f32 v[78:79], v[72:73], v[78:79], v[88:89]
	v_add_f32_e32 v72, 1.0, v75
	v_exp_f32_e32 v64, v64
	v_exp_f32_e32 v65, v65
	v_mul_f32_e32 v70, 0xbfb8aa3b, v70
	v_mul_f32_e32 v66, v66, v81
	v_mul_f32_e32 v71, 0xbfb8aa3b, v71
	v_mul_f32_e32 v67, v67, v81
	v_rcp_f32_e32 v75, v72
	v_exp_f32_e32 v70, v70
	v_mul_f32_e32 v66, 0xbfb8aa3b, v66
	v_exp_f32_e32 v71, v71
	v_mul_f32_e32 v67, 0xbfb8aa3b, v67
	v_exp_f32_e32 v66, v66
	v_exp_f32_e32 v67, v67
	v_add_f32_e32 v68, 1.0, v68
	v_add_f32_e32 v69, 1.0, v69
	v_lshlrev_b32_e32 v72, 16, v135
	v_and_b32_e32 v73, 0xffff0000, v135
	v_lshlrev_b32_e32 v88, 16, v131
	v_and_b32_e32 v89, 0xffff0000, v131
	v_rcp_f32_e32 v68, v68
	v_add_f32_e32 v64, 1.0, v64
	v_rcp_f32_e32 v69, v69
	v_add_f32_e32 v65, 1.0, v65
	v_pk_fma_f32 v[88:89], v[74:75], v[72:73], v[88:89]
	v_rcp_f32_e32 v64, v64
	v_rcp_f32_e32 v65, v65
	v_add_f32_e32 v70, 1.0, v70
	v_add_f32_e32 v71, 1.0, v71
	v_pk_mul_f32 v[72:73], v[88:89], v[88:89]
	v_rcp_f32_e32 v70, v70
	v_add_f32_e32 v66, 1.0, v66
	v_rcp_f32_e32 v71, v71
	v_add_f32_e32 v67, 1.0, v67
	v_pk_fma_f32 v[90:91], v[78:79], v[78:79], v[72:73]
	v_cvt_pk_bf16_f32 v72, v76, v77
	v_cvt_pk_bf16_f32 v73, v78, v79
	s_waitcnt vmcnt(6)
	v_lshlrev_b32_e32 v76, 16, v116
	v_and_b32_e32 v77, 0xffff0000, v116
	v_lshlrev_b32_e32 v78, 16, v112
	v_and_b32_e32 v79, 0xffff0000, v112
	v_rcp_f32_e32 v66, v66
	v_rcp_f32_e32 v67, v67
	v_pk_fma_f32 v[68:69], v[68:69], v[76:77], v[78:79]
	v_lshlrev_b32_e32 v76, 16, v118
	v_and_b32_e32 v77, 0xffff0000, v118
	v_lshlrev_b32_e32 v78, 16, v114
	v_and_b32_e32 v79, 0xffff0000, v114
	v_cvt_pk_bf16_f32 v74, v84, v85
	v_pk_fma_f32 v[76:77], v[64:65], v[76:77], v[78:79]
	v_lshlrev_b32_e32 v78, 16, v117
	v_and_b32_e32 v79, 0xffff0000, v117
	v_lshlrev_b32_e32 v84, 16, v113
	v_and_b32_e32 v85, 0xffff0000, v113
	v_add_f32_e32 v81, v86, v87
	v_pk_mul_f32 v[64:65], v[76:77], v[76:77]
	v_pk_fma_f32 v[70:71], v[70:71], v[78:79], v[84:85]
	v_lshlrev_b32_e32 v78, 16, v119
	v_and_b32_e32 v79, 0xffff0000, v119
	v_lshlrev_b32_e32 v84, 16, v115
	v_and_b32_e32 v85, 0xffff0000, v115
	v_add_f32_e32 v81, v90, v81
	v_pk_fma_f32 v[64:65], v[68:69], v[68:69], v[64:65]
	v_pk_fma_f32 v[78:79], v[66:67], v[78:79], v[84:85]
	v_add_f32_e32 v81, v91, v81
	v_pk_mul_f32 v[66:67], v[78:79], v[78:79]
	v_add_f32_e32 v64, v64, v81
	v_pk_fma_f32 v[66:67], v[70:71], v[70:71], v[66:67]
	v_add_f32_e32 v64, v65, v64
	v_add_f32_e32 v64, v66, v64
	v_add_f32_e32 v67, v67, v64
	ds_bpermute_b32 v81, v187, v67
	v_lshl_add_u64 v[64:65], s[18:19], 0, v[82:83]
	v_lshl_add_u64 v[82:83], v[202:203], 1, v[64:65]
	v_cvt_pk_bf16_f32 v75, v88, v89
	v_cvt_pk_bf16_f32 v66, v68, v69
	s_waitcnt lgkmcnt(0)
	v_add_f32_e32 v64, v67, v81
	ds_bpermute_b32 v65, v189, v64
	v_cvt_pk_bf16_f32 v67, v70, v71
	v_cvt_pk_bf16_f32 v68, v76, v77
	v_cvt_pk_bf16_f32 v69, v78, v79
	global_store_dwordx4 v[82:83], v[72:75], off
	global_store_dwordx4 v[82:83], v[66:69], off offset:256
	s_and_saveexec_b64 s[0:1], vcc
	s_cbranch_execz .LBB0_571
	s_waitcnt lgkmcnt(0)
	v_add_f32_e32 v64, v64, v65
	v_lshl_add_u32 v65, v80, 2, 0
	v_add_u32_e32 v65, 0x20400, v65
	ds_add_f32 v65, v64
